# grid barrier: L1/L2 invalidate issued at arrival (overlaps the wait) instead of after release
# speedup vs baseline: 1.0791x; 1.0099x over previous
; __device__ __forceinline__ unsigned xb_ld(unsigned* p)              { return __hip_atomic_load(p, __ATOMIC_RELAXED, __HIP_MEMORY_SCOPE_AGENT); }
; __device__ __forceinline__ unsigned xb_add(unsigned* p, unsigned v) { return __hip_atomic_fetch_add(p, v, __ATOMIC_RELAXED, __HIP_MEMORY_SCOPE_AGENT); }
; #define XB_SPIN(cond, bar) do { unsigned _sp = 0; while (cond) { __builtin_amdgcn_s_sleep(1); \
;     if ((++_sp & 255u) == 0u) { if (xb_ld(&(bar)[XB_TMO])) break; if (_sp > XB_SPIN_CAP) { atomicAdd(&(bar)[XB_TMO], 1u); break; } } } } while (0)
; __device__ __forceinline__ void xcd_barrier(const XcdBarrier& b) {
;     ...
;         unsigned nloc = b.st[0], nx = b.st[1];
;         if (nloc == 0u) { xcd_barrier_complete(bar, b.x, nloc, nx); b.st[0] = nloc; b.st[1] = nx; }
;         const unsigned old = xb_add(&bar[XB_XSUB(b.x)], 1u);
;         const unsigned gen = old / nloc;
;         if (old + 1u == (gen + 1u) * nloc) {
;             __builtin_amdgcn_fence(__ATOMIC_RELEASE, "agent");
;             asm volatile("s_waitcnt vmcnt(0)" ::: "memory");
;             const unsigned og = xb_add(&bar[XB_TOP], 1u);
;             const unsigned tg = og / nx;
;             if (og + 1u == (tg + 1u) * nx) xb_add(&bar[XB_TOPGEN], 1u);
;             else XB_SPIN(xb_ld(&bar[XB_TOPGEN]) == tg, bar);
;             __builtin_amdgcn_fence(__ATOMIC_ACQUIRE, "agent");
;             xb_add(&bar[XB_XGEN(b.x)], 1u);
;             asm volatile("s_waitcnt vmcnt(0)" ::: "memory");
;         } else {
;             XB_SPIN(xb_ld(&bar[XB_XGEN(b.x)]) == gen, bar);
.LBB0_70:
	s_or_b64 exec, exec, s[8:9]
	v_cvt_f32_u32_e32 v5, v3
	s_waitcnt vmcnt(0)
	v_readfirstlane_b32 s2, v4
	v_sub_u32_e32 v4, 0, v3
	v_rcp_iflag_f32_e32 v5, v5
	v_add_u32_e32 v6, s2, v2
	v_mul_f32_e32 v5, 0x4f7ffffe, v5
	v_cvt_u32_f32_e32 v5, v5
	v_mul_lo_u32 v2, v4, v5
	v_mul_hi_u32 v2, v5, v2
	v_add_u32_e32 v2, v5, v2
	v_mul_hi_u32 v2, v6, v2
	v_mul_lo_u32 v4, v2, v3
	v_sub_u32_e32 v4, v6, v4
	v_add_u32_e32 v5, 1, v2
	v_cmp_ge_u32_e32 vcc, v4, v3
	s_nop 1
	v_cndmask_b32_e32 v2, v2, v5, vcc
	v_sub_u32_e32 v5, v4, v3
	v_cndmask_b32_e32 v4, v4, v5, vcc
	v_add_u32_e32 v5, 1, v2
	v_cmp_ge_u32_e32 vcc, v4, v3
	v_add_u32_e32 v4, 1, v6
	s_nop 0
	v_cndmask_b32_e32 v2, v2, v5, vcc
	v_mul_lo_u32 v5, v3, v2
	v_add_u32_e32 v3, v5, v3
	v_cmp_ne_u32_e32 vcc, v4, v3
	s_and_saveexec_b64 s[2:3], vcc
	s_xor_b64 s[8:9], exec, s[2:3]
	s_cbranch_execz .LBB0_84
	buffer_inv sc1
	s_waitcnt lgkmcnt(0)
	v_mov_b32_e32 v1, 0x2000
	global_load_dword v1, v1, s[6:7] offset:1024 sc1
	s_add_u32 s14, s6, 0x2400
	s_addc_u32 s15, s7, 0
	s_waitcnt vmcnt(0)
	v_cmp_eq_u32_e32 vcc, v1, v2
	s_and_saveexec_b64 s[10:11], vcc
	s_cbranch_execz .LBB0_83
	s_add_u32 s12, s66, 0x4200
	s_addc_u32 s13, s67, 0
	s_mov_b32 s24, 1
	s_mov_b64 s[16:17], 0
	v_mov_b32_e32 v1, 0
	s_branch .LBB0_74

; __device__ __forceinline__ unsigned xb_ld(unsigned* p)              { return __hip_atomic_load(p, __ATOMIC_RELAXED, __HIP_MEMORY_SCOPE_AGENT); }
; __device__ __forceinline__ unsigned xb_add(unsigned* p, unsigned v) { return __hip_atomic_fetch_add(p, v, __ATOMIC_RELAXED, __HIP_MEMORY_SCOPE_AGENT); }
; #define XB_SPIN(cond, bar) do { unsigned _sp = 0; while (cond) { __builtin_amdgcn_s_sleep(1); \
;     if ((++_sp & 255u) == 0u) { if (xb_ld(&(bar)[XB_TMO])) break; if (_sp > XB_SPIN_CAP) { atomicAdd(&(bar)[XB_TMO], 1u); break; } } } } while (0)
; __device__ __forceinline__ void xcd_barrier(const XcdBarrier& b) {
;     ...
;         if (old + 1u == (gen + 1u) * nloc) {
;             __builtin_amdgcn_fence(__ATOMIC_RELEASE, "agent");
;             asm volatile("s_waitcnt vmcnt(0)" ::: "memory");
;             const unsigned og = xb_add(&bar[XB_TOP], 1u);
;             const unsigned tg = og / nx;
;             if (og + 1u == (tg + 1u) * nx) xb_add(&bar[XB_TOPGEN], 1u);
;             else XB_SPIN(xb_ld(&bar[XB_TOPGEN]) == tg, bar);
;     ...
;             XB_SPIN(xb_ld(&bar[XB_XGEN(b.x)]) == gen, bar);
;             __builtin_amdgcn_fence(__ATOMIC_ACQUIRE, "agent");
;             asm volatile("s_waitcnt vmcnt(0)" ::: "memory");
.LBB0_83:
	s_or_b64 exec, exec, s[10:11]
	s_waitcnt vmcnt(0)
	s_waitcnt vmcnt(0)
.LBB0_84:
	s_andn2_saveexec_b64 s[2:3], s[8:9]
	s_cbranch_execz .LBB0_104
	s_mov_b64 s[2:3], exec
	buffer_wbl2 sc1
	s_waitcnt lgkmcnt(0)
	s_waitcnt vmcnt(0)
	buffer_inv sc1
	v_mbcnt_lo_u32_b32 v2, s2, 0
	v_mbcnt_hi_u32_b32 v2, s3, v2
	v_cmp_eq_u32_e32 vcc, 0, v2
	s_and_saveexec_b64 s[8:9], vcc
	s_cbranch_execz .LBB0_87
	s_bcnt1_i32_b64 s2, s[2:3]
	v_mov_b32_e32 v3, 0x7000
	v_mov_b32_e32 v4, s2
	global_atomic_add v3, v3, v4, s[66:67] offset:1024 sc0

; __device__ __forceinline__ unsigned xb_ld(unsigned* p)              { return __hip_atomic_load(p, __ATOMIC_RELAXED, __HIP_MEMORY_SCOPE_AGENT); }
; __device__ __forceinline__ unsigned xb_add(unsigned* p, unsigned v) { return __hip_atomic_fetch_add(p, v, __ATOMIC_RELAXED, __HIP_MEMORY_SCOPE_AGENT); }
; #define XB_SPIN(cond, bar) do { unsigned _sp = 0; while (cond) { __builtin_amdgcn_s_sleep(1); \
;     if ((++_sp & 255u) == 0u) { if (xb_ld(&(bar)[XB_TMO])) break; if (_sp > XB_SPIN_CAP) { atomicAdd(&(bar)[XB_TMO], 1u); break; } } } } while (0)
; __device__ __forceinline__ void xcd_barrier(const XcdBarrier& b) {
;     ...
;             else XB_SPIN(xb_ld(&bar[XB_TOPGEN]) == tg, bar);
;             __builtin_amdgcn_fence(__ATOMIC_ACQUIRE, "agent");
;             xb_add(&bar[XB_XGEN(b.x)], 1u);
.LBB0_101:
	s_or_b64 exec, exec, s[8:9]
	s_mov_b64 s[2:3], exec
	v_mbcnt_lo_u32_b32 v1, s2, 0
	v_mbcnt_hi_u32_b32 v1, s3, v1
	v_cmp_eq_u32_e32 vcc, 0, v1
	s_waitcnt vmcnt(0)
	s_and_saveexec_b64 s[8:9], vcc
	s_cbranch_execz .LBB0_103
	s_bcnt1_i32_b64 s2, s[2:3]
	v_mov_b32_e32 v1, 0x2000
	v_mov_b32_e32 v2, s2
	global_atomic_add v1, v2, s[6:7] offset:1024

; __device__ __forceinline__ unsigned xb_ld(unsigned* p)              { return __hip_atomic_load(p, __ATOMIC_RELAXED, __HIP_MEMORY_SCOPE_AGENT); }
; __device__ __forceinline__ unsigned xb_add(unsigned* p, unsigned v) { return __hip_atomic_fetch_add(p, v, __ATOMIC_RELAXED, __HIP_MEMORY_SCOPE_AGENT); }
; #define XB_SPIN(cond, bar) do { unsigned _sp = 0; while (cond) { __builtin_amdgcn_s_sleep(1); \
;     if ((++_sp & 255u) == 0u) { if (xb_ld(&(bar)[XB_TMO])) break; if (_sp > XB_SPIN_CAP) { atomicAdd(&(bar)[XB_TMO], 1u); break; } } } } while (0)
; __device__ __forceinline__ void xcd_barrier(const XcdBarrier& b) {
;     ...
;         unsigned nloc = b.st[0], nx = b.st[1];
;         if (nloc == 0u) { xcd_barrier_complete(bar, b.x, nloc, nx); b.st[0] = nloc; b.st[1] = nx; }
;         const unsigned old = xb_add(&bar[XB_XSUB(b.x)], 1u);
;         const unsigned gen = old / nloc;
;         if (old + 1u == (gen + 1u) * nloc) {
;             __builtin_amdgcn_fence(__ATOMIC_RELEASE, "agent");
;             asm volatile("s_waitcnt vmcnt(0)" ::: "memory");
;             const unsigned og = xb_add(&bar[XB_TOP], 1u);
;             const unsigned tg = og / nx;
;             if (og + 1u == (tg + 1u) * nx) xb_add(&bar[XB_TOPGEN], 1u);
;             else XB_SPIN(xb_ld(&bar[XB_TOPGEN]) == tg, bar);
;             __builtin_amdgcn_fence(__ATOMIC_ACQUIRE, "agent");
;             xb_add(&bar[XB_XGEN(b.x)], 1u);
;             asm volatile("s_waitcnt vmcnt(0)" ::: "memory");
;         } else {
;             XB_SPIN(xb_ld(&bar[XB_XGEN(b.x)]) == gen, bar);
.LBB0_155:
	s_or_b64 exec, exec, s[6:7]
	v_cvt_f32_u32_e32 v6, v4
	s_waitcnt vmcnt(0)
	v_readfirstlane_b32 s2, v5
	v_sub_u32_e32 v5, 0, v4
	v_rcp_iflag_f32_e32 v6, v6
	v_add_u32_e32 v7, s2, v3
	v_mul_f32_e32 v6, 0x4f7ffffe, v6
	v_cvt_u32_f32_e32 v6, v6
	v_mul_lo_u32 v3, v5, v6
	v_mul_hi_u32 v3, v6, v3
	v_add_u32_e32 v3, v6, v3
	v_mul_hi_u32 v3, v7, v3
	v_mul_lo_u32 v5, v3, v4
	v_sub_u32_e32 v5, v7, v5
	v_add_u32_e32 v6, 1, v3
	v_cmp_ge_u32_e32 vcc, v5, v4
	s_nop 1
	v_cndmask_b32_e32 v3, v3, v6, vcc
	v_sub_u32_e32 v6, v5, v4
	v_cndmask_b32_e32 v5, v5, v6, vcc
	v_add_u32_e32 v6, 1, v3
	v_cmp_ge_u32_e32 vcc, v5, v4
	v_add_u32_e32 v5, 1, v7
	s_nop 0
	v_cndmask_b32_e32 v3, v3, v6, vcc
	v_mul_lo_u32 v6, v4, v3
	v_add_u32_e32 v4, v6, v4
	v_cmp_ne_u32_e32 vcc, v5, v4
	s_and_saveexec_b64 s[2:3], vcc
	s_xor_b64 s[6:7], exec, s[2:3]
	s_cbranch_execz .LBB0_169
	buffer_inv sc1
	v_readlane_b32 s2, v253, 29
	v_readlane_b32 s3, v253, 30
	s_waitcnt lgkmcnt(0)
	s_nop 3
	global_load_dword v2, v167, s[2:3] sc1
	s_waitcnt vmcnt(0)
	v_cmp_eq_u32_e32 vcc, v2, v3
	s_and_saveexec_b64 s[8:9], vcc
	s_cbranch_execz .LBB0_168
	s_mov_b32 s2, 1
	s_mov_b64 s[10:11], 0
	s_branch .LBB0_159

; __device__ __forceinline__ unsigned xb_ld(unsigned* p)              { return __hip_atomic_load(p, __ATOMIC_RELAXED, __HIP_MEMORY_SCOPE_AGENT); }
; __device__ __forceinline__ unsigned xb_add(unsigned* p, unsigned v) { return __hip_atomic_fetch_add(p, v, __ATOMIC_RELAXED, __HIP_MEMORY_SCOPE_AGENT); }
; #define XB_SPIN(cond, bar) do { unsigned _sp = 0; while (cond) { __builtin_amdgcn_s_sleep(1); \
;     if ((++_sp & 255u) == 0u) { if (xb_ld(&(bar)[XB_TMO])) break; if (_sp > XB_SPIN_CAP) { atomicAdd(&(bar)[XB_TMO], 1u); break; } } } } while (0)
; __device__ __forceinline__ void xcd_barrier(const XcdBarrier& b) {
;     ...
;         if (old + 1u == (gen + 1u) * nloc) {
;             __builtin_amdgcn_fence(__ATOMIC_RELEASE, "agent");
;             asm volatile("s_waitcnt vmcnt(0)" ::: "memory");
;             const unsigned og = xb_add(&bar[XB_TOP], 1u);
;             const unsigned tg = og / nx;
;             if (og + 1u == (tg + 1u) * nx) xb_add(&bar[XB_TOPGEN], 1u);
;             else XB_SPIN(xb_ld(&bar[XB_TOPGEN]) == tg, bar);
;     ...
;             XB_SPIN(xb_ld(&bar[XB_XGEN(b.x)]) == gen, bar);
;             __builtin_amdgcn_fence(__ATOMIC_ACQUIRE, "agent");
;             asm volatile("s_waitcnt vmcnt(0)" ::: "memory");
.LBB0_168:
	s_or_b64 exec, exec, s[8:9]
	s_waitcnt vmcnt(0)
	s_waitcnt vmcnt(0)
.LBB0_169:
	s_andn2_saveexec_b64 s[2:3], s[6:7]
	s_cbranch_execz .LBB0_189
	s_mov_b64 s[6:7], exec
	buffer_wbl2 sc1
	s_waitcnt lgkmcnt(0)
	s_waitcnt vmcnt(0)
	buffer_inv sc1
	v_mbcnt_lo_u32_b32 v3, s6, 0
	v_mbcnt_hi_u32_b32 v3, s7, v3
	v_cmp_eq_u32_e32 vcc, 0, v3
	s_and_saveexec_b64 s[8:9], vcc
	s_cbranch_execz .LBB0_172
	s_bcnt1_i32_b64 s2, s[6:7]
	v_mov_b32_e32 v4, s2
	v_readlane_b32 s2, v253, 31
	v_readlane_b32 s3, v253, 32
	s_nop 4
	global_atomic_add v4, v167, v4, s[2:3] sc0

; __device__ __forceinline__ unsigned xb_ld(unsigned* p)              { return __hip_atomic_load(p, __ATOMIC_RELAXED, __HIP_MEMORY_SCOPE_AGENT); }
; __device__ __forceinline__ unsigned xb_add(unsigned* p, unsigned v) { return __hip_atomic_fetch_add(p, v, __ATOMIC_RELAXED, __HIP_MEMORY_SCOPE_AGENT); }
; #define XB_SPIN(cond, bar) do { unsigned _sp = 0; while (cond) { __builtin_amdgcn_s_sleep(1); \
;     if ((++_sp & 255u) == 0u) { if (xb_ld(&(bar)[XB_TMO])) break; if (_sp > XB_SPIN_CAP) { atomicAdd(&(bar)[XB_TMO], 1u); break; } } } } while (0)
; __device__ __forceinline__ void xcd_barrier(const XcdBarrier& b) {
;     ...
;             else XB_SPIN(xb_ld(&bar[XB_TOPGEN]) == tg, bar);
;             __builtin_amdgcn_fence(__ATOMIC_ACQUIRE, "agent");
;             xb_add(&bar[XB_XGEN(b.x)], 1u);
.LBB0_186:
	s_or_b64 exec, exec, s[6:7]
	s_mov_b64 s[6:7], exec
	v_mbcnt_lo_u32_b32 v2, s6, 0
	v_mbcnt_hi_u32_b32 v2, s7, v2
	v_cmp_eq_u32_e32 vcc, 0, v2
	s_waitcnt vmcnt(0)
	s_and_saveexec_b64 s[8:9], vcc
	s_cbranch_execz .LBB0_188
	s_bcnt1_i32_b64 s2, s[6:7]
	v_mov_b32_e32 v2, s2
	v_readlane_b32 s2, v253, 29
	v_readlane_b32 s3, v253, 30
	s_nop 4
	global_atomic_add v167, v2, s[2:3]

; __device__ __forceinline__ unsigned xb_ld(unsigned* p)              { return __hip_atomic_load(p, __ATOMIC_RELAXED, __HIP_MEMORY_SCOPE_AGENT); }
; __device__ __forceinline__ unsigned xb_add(unsigned* p, unsigned v) { return __hip_atomic_fetch_add(p, v, __ATOMIC_RELAXED, __HIP_MEMORY_SCOPE_AGENT); }
; #define XB_SPIN(cond, bar) do { unsigned _sp = 0; while (cond) { __builtin_amdgcn_s_sleep(1); \
;     if ((++_sp & 255u) == 0u) { if (xb_ld(&(bar)[XB_TMO])) break; if (_sp > XB_SPIN_CAP) { atomicAdd(&(bar)[XB_TMO], 1u); break; } } } } while (0)
; __device__ __forceinline__ void xcd_barrier(const XcdBarrier& b) {
;     ...
;         unsigned nloc = b.st[0], nx = b.st[1];
;         if (nloc == 0u) { xcd_barrier_complete(bar, b.x, nloc, nx); b.st[0] = nloc; b.st[1] = nx; }
;         const unsigned old = xb_add(&bar[XB_XSUB(b.x)], 1u);
;         const unsigned gen = old / nloc;
;         if (old + 1u == (gen + 1u) * nloc) {
;             __builtin_amdgcn_fence(__ATOMIC_RELEASE, "agent");
;             asm volatile("s_waitcnt vmcnt(0)" ::: "memory");
;             const unsigned og = xb_add(&bar[XB_TOP], 1u);
;             const unsigned tg = og / nx;
;             if (og + 1u == (tg + 1u) * nx) xb_add(&bar[XB_TOPGEN], 1u);
;             else XB_SPIN(xb_ld(&bar[XB_TOPGEN]) == tg, bar);
;             __builtin_amdgcn_fence(__ATOMIC_ACQUIRE, "agent");
;             xb_add(&bar[XB_XGEN(b.x)], 1u);
;             asm volatile("s_waitcnt vmcnt(0)" ::: "memory");
;         } else {
;             XB_SPIN(xb_ld(&bar[XB_XGEN(b.x)]) == gen, bar);
.LBB0_237:
	s_or_b64 exec, exec, s[6:7]
	v_cvt_f32_u32_e32 v6, v4
	s_waitcnt vmcnt(0)
	v_readfirstlane_b32 s0, v5
	v_sub_u32_e32 v5, 0, v4
	v_rcp_iflag_f32_e32 v6, v6
	v_add_u32_e32 v7, s0, v3
	v_mul_f32_e32 v6, 0x4f7ffffe, v6
	v_cvt_u32_f32_e32 v6, v6
	v_mul_lo_u32 v3, v5, v6
	v_mul_hi_u32 v3, v6, v3
	v_add_u32_e32 v3, v6, v3
	v_mul_hi_u32 v3, v7, v3
	v_mul_lo_u32 v5, v3, v4
	v_sub_u32_e32 v5, v7, v5
	v_add_u32_e32 v6, 1, v3
	v_cmp_ge_u32_e32 vcc, v5, v4
	s_nop 1
	v_cndmask_b32_e32 v3, v3, v6, vcc
	v_sub_u32_e32 v6, v5, v4
	v_cndmask_b32_e32 v5, v5, v6, vcc
	v_add_u32_e32 v6, 1, v3
	v_cmp_ge_u32_e32 vcc, v5, v4
	v_add_u32_e32 v5, 1, v7
	s_nop 0
	v_cndmask_b32_e32 v3, v3, v6, vcc
	v_mul_lo_u32 v6, v4, v3
	v_add_u32_e32 v4, v6, v4
	v_cmp_ne_u32_e32 vcc, v5, v4
	s_and_saveexec_b64 s[2:3], vcc
	s_xor_b64 s[6:7], exec, s[2:3]
	s_cbranch_execz .LBB0_251
	buffer_inv sc1
	v_readlane_b32 s2, v253, 29
	v_readlane_b32 s3, v253, 30
	s_waitcnt lgkmcnt(0)
	s_nop 3
	global_load_dword v2, v167, s[2:3] sc1
	s_waitcnt vmcnt(0)
	v_cmp_eq_u32_e32 vcc, v2, v3
	s_and_saveexec_b64 s[8:9], vcc
	s_cbranch_execz .LBB0_250
	s_mov_b32 s0, 1
	s_mov_b64 s[10:11], 0
	s_branch .LBB0_241

; __device__ __forceinline__ unsigned xb_ld(unsigned* p)              { return __hip_atomic_load(p, __ATOMIC_RELAXED, __HIP_MEMORY_SCOPE_AGENT); }
; __device__ __forceinline__ unsigned xb_add(unsigned* p, unsigned v) { return __hip_atomic_fetch_add(p, v, __ATOMIC_RELAXED, __HIP_MEMORY_SCOPE_AGENT); }
; #define XB_SPIN(cond, bar) do { unsigned _sp = 0; while (cond) { __builtin_amdgcn_s_sleep(1); \
;     if ((++_sp & 255u) == 0u) { if (xb_ld(&(bar)[XB_TMO])) break; if (_sp > XB_SPIN_CAP) { atomicAdd(&(bar)[XB_TMO], 1u); break; } } } } while (0)
; __device__ __forceinline__ void xcd_barrier(const XcdBarrier& b) {
;     ...
;             __builtin_amdgcn_fence(__ATOMIC_RELEASE, "agent");
;             asm volatile("s_waitcnt vmcnt(0)" ::: "memory");
;             const unsigned og = xb_add(&bar[XB_TOP], 1u);
;             const unsigned tg = og / nx;
;             if (og + 1u == (tg + 1u) * nx) xb_add(&bar[XB_TOPGEN], 1u);
;             else XB_SPIN(xb_ld(&bar[XB_TOPGEN]) == tg, bar);
.LBB0_251:
	s_andn2_saveexec_b64 s[2:3], s[6:7]
	s_cbranch_execz .LBB0_271
	s_mov_b64 s[6:7], exec
	buffer_wbl2 sc1
	s_waitcnt lgkmcnt(0)
	s_waitcnt vmcnt(0)
	buffer_inv sc1
	v_mbcnt_lo_u32_b32 v3, s6, 0
	v_mbcnt_hi_u32_b32 v3, s7, v3
	v_cmp_eq_u32_e32 vcc, 0, v3
	s_and_saveexec_b64 s[8:9], vcc
	s_cbranch_execz .LBB0_254
	s_bcnt1_i32_b64 s0, s[6:7]
	v_readlane_b32 s2, v253, 31
	v_mov_b32_e32 v4, s0
	v_readlane_b32 s3, v253, 32
	s_nop 4
	global_atomic_add v4, v167, v4, s[2:3] sc0

; __device__ __forceinline__ unsigned xb_ld(unsigned* p)              { return __hip_atomic_load(p, __ATOMIC_RELAXED, __HIP_MEMORY_SCOPE_AGENT); }
; __device__ __forceinline__ unsigned xb_add(unsigned* p, unsigned v) { return __hip_atomic_fetch_add(p, v, __ATOMIC_RELAXED, __HIP_MEMORY_SCOPE_AGENT); }
; #define XB_SPIN(cond, bar) do { unsigned _sp = 0; while (cond) { __builtin_amdgcn_s_sleep(1); \
;     if ((++_sp & 255u) == 0u) { if (xb_ld(&(bar)[XB_TMO])) break; if (_sp > XB_SPIN_CAP) { atomicAdd(&(bar)[XB_TMO], 1u); break; } } } } while (0)
; __device__ __forceinline__ void xcd_barrier(const XcdBarrier& b) {
;     ...
;             else XB_SPIN(xb_ld(&bar[XB_TOPGEN]) == tg, bar);
;             __builtin_amdgcn_fence(__ATOMIC_ACQUIRE, "agent");
;             xb_add(&bar[XB_XGEN(b.x)], 1u);
.LBB0_268:
	s_or_b64 exec, exec, s[6:7]
	s_mov_b64 s[6:7], exec
	v_mbcnt_lo_u32_b32 v2, s6, 0
	v_mbcnt_hi_u32_b32 v2, s7, v2
	v_cmp_eq_u32_e32 vcc, 0, v2
	s_waitcnt vmcnt(0)
	s_and_saveexec_b64 s[8:9], vcc
	s_cbranch_execz .LBB0_270
	s_bcnt1_i32_b64 s0, s[6:7]
	v_readlane_b32 s2, v253, 29
	v_mov_b32_e32 v2, s0
	v_readlane_b32 s3, v253, 30
	s_nop 4
	global_atomic_add v167, v2, s[2:3]

; __device__ __forceinline__ unsigned xb_ld(unsigned* p)              { return __hip_atomic_load(p, __ATOMIC_RELAXED, __HIP_MEMORY_SCOPE_AGENT); }
; __device__ __forceinline__ unsigned xb_add(unsigned* p, unsigned v) { return __hip_atomic_fetch_add(p, v, __ATOMIC_RELAXED, __HIP_MEMORY_SCOPE_AGENT); }
; #define XB_SPIN(cond, bar) do { unsigned _sp = 0; while (cond) { __builtin_amdgcn_s_sleep(1); \
;     if ((++_sp & 255u) == 0u) { if (xb_ld(&(bar)[XB_TMO])) break; if (_sp > XB_SPIN_CAP) { atomicAdd(&(bar)[XB_TMO], 1u); break; } } } } while (0)
; __device__ __forceinline__ void xcd_barrier(const XcdBarrier& b) {
;     ...
;             else XB_SPIN(xb_ld(&bar[XB_TOPGEN]) == tg, bar);
;             __builtin_amdgcn_fence(__ATOMIC_ACQUIRE, "agent");
;             xb_add(&bar[XB_XGEN(b.x)], 1u);
.LBB0_825:
	s_or_b64 exec, exec, s[6:7]
	s_mov_b64 s[6:7], exec
	v_mbcnt_lo_u32_b32 v2, s6, 0
	v_mbcnt_hi_u32_b32 v2, s7, v2
	v_cmp_eq_u32_e32 vcc, 0, v2
	s_waitcnt vmcnt(0)
	s_and_saveexec_b64 s[8:9], vcc
	s_cbranch_execz .LBB0_106
	s_bcnt1_i32_b64 s0, s[6:7]
	v_readlane_b32 s2, v253, 29
	v_mov_b32_e32 v2, s0
	v_readlane_b32 s3, v253, 30
	s_nop 4
	global_atomic_add v167, v2, s[2:3]
	s_branch .LBB0_106
